# v18 + P6 epilogues un-aligned (template default): halves run EpiAct one after the other beside the partner's MFMA/load work
# baseline (speedup 1.0000x reference)
; __device__ __forceinline__ unsigned cvt_pk_bf16(float lo, float hi) { unsigned r; asm volatile("v_cvt_pk_bf16_f32 %0, %1, %2" : "=v"(r) : "v"(lo), "v"(hi)); return r; }
; #define LAS __attribute__((address_space(3)))
; __device__ __forceinline__ float siluf_(float x) { return x * __builtin_amdgcn_rcpf(1.0f + __builtin_amdgcn_exp2f(-1.4426950408889634f * x)); }
; __device__ __forceinline__ float rstd_of(float ss) { return __builtin_amdgcn_rsqf(ss * (1.0f / DM) + EPS); }
;     __device__ __forceinline__ void operator()(const pg8::f32x4 (&acc)[2][2][4][2], const Unit& u, int wr, int wc, int fr, int fq) const {
;         const int row0 = u.pm * BM + wr * 64, lane = fr + 16 * fq, rr = lane >> 2, sl = lane & 3;
;         LAS unsigned char* W = scr + (wr * 4 + wc) * 2048;
;         bf16* outp = ACT + (size_t)(row0 + rr) * DFF + u.pn * HALF + wc * 32 + sl * 8;
; #pragma unroll
;         for (int ai = 0; ai < 2; ++ai)
; #pragma unroll
;             for (int m = 0; m < 4; ++m) { const int rg = ai * HALF + m * 16; const float rs = rstd_of(SS1[row0 + rg + fr]);
;                 const pg8::f32x4 g0 = acc[ai][0][m][0] * rs, g1 = acc[ai][0][m][1] * rs, u0 = acc[ai][1][m][0] * rs, u1 = acc[ai][1][m][1] * rs;
;                 u32x4 w; w.x = cvt_pk_bf16(siluf_(g0[0]) * u0[0], siluf_(g0[1]) * u0[1]); w.y = cvt_pk_bf16(siluf_(g0[2]) * u0[2], siluf_(g0[3]) * u0[3]);
;                 w.z = cvt_pk_bf16(siluf_(g1[0]) * u1[0], siluf_(g1[1]) * u1[1]); w.w = cvt_pk_bf16(siluf_(g1[2]) * u1[2], siluf_(g1[3]) * u1[3]);
;                 *(LAS u32x4*)epi_slot(W, fr, fq + 4 * (m & 1)) = w;
;                 const u32x4 o = *(const LAS u32x4*)epi_slot(W, rr, sl + 4 * (m & 1));
;                 *(u32x4*)(outp + (size_t)rg * DFF) = o; }
.LBB0_880:
	s_lshl_b32 s4, s4, 8
	s_add_i32 s21, s4, s42
	v_or_b32_e32 v148, s21, v152
	v_ashrrev_i32_e32 v149, 31, v148
	v_lshl_add_u64 v[150:151], v[148:149], 2, s[14:15]
	global_load_dword v149, v[150:151], off
	global_load_dword v201, v[150:151], off offset:64
	global_load_dword v202, v[150:151], off offset:128
	global_load_dword v203, v[150:151], off offset:192
	global_load_dword v204, v[150:151], off offset:512
	global_load_dword v205, v[150:151], off offset:576
	global_load_dword v206, v[150:151], off offset:640
	global_load_dword v207, v[150:151], off offset:704
	v_mov_b64_e32 v[164:165], s[56:57]
	s_lshl_b32 s4, s5, 7
	s_ashr_i32 s5, s4, 31
	s_waitcnt vmcnt(7)
	v_fmamk_f32 v149, v149, 0x3a800000, v159
	v_rsq_f32_e32 v166, v149
	v_or_b32_e32 v149, s21, v153
	v_pk_mul_f32 v[124:125], v[124:125], v[166:167] op_sel_hi:[1,0]
	v_pk_mul_f32 v[128:129], v[128:129], v[166:167] op_sel_hi:[1,0]
	v_pk_mul_f32 v[126:127], v[126:127], v[166:167] op_sel_hi:[1,0]
	v_pk_mul_f32 v[122:123], v[122:123], v[166:167] op_sel_hi:[1,0]
	v_mul_f32_e32 v173, 0xbfb8aa3b, v125
	v_pk_mul_f32 v[120:121], v[120:121], v[166:167] op_sel_hi:[1,0]
	v_pk_mul_f32 v[118:119], v[118:119], v[166:167] op_sel_hi:[1,0]
	v_pk_mul_f32 v[116:117], v[116:117], v[166:167] op_sel_hi:[1,0]
	v_pk_mul_f32 v[114:115], v[114:115], v[166:167] op_sel_hi:[1,0]
	v_mul_f32_e32 v166, 0xbfb8aa3b, v126
	v_mul_f32_e32 v167, 0xbfb8aa3b, v127
	v_mul_f32_e32 v168, 0xbfb8aa3b, v128
	v_mul_f32_e32 v169, 0xbfb8aa3b, v129
	v_mul_f32_e32 v170, 0xbfb8aa3b, v122
	v_mul_f32_e32 v171, 0xbfb8aa3b, v123
	v_mul_f32_e32 v172, 0xbfb8aa3b, v124
	v_exp_f32_e32 v173, v173
	v_exp_f32_e32 v166, v166
	v_exp_f32_e32 v167, v167
	v_exp_f32_e32 v168, v168
	v_exp_f32_e32 v169, v169
	v_exp_f32_e32 v170, v170
	v_exp_f32_e32 v171, v171
	v_exp_f32_e32 v172, v172
	v_add_f32_e32 v173, 1.0, v173
	v_add_f32_e32 v166, 1.0, v166
	v_add_f32_e32 v167, 1.0, v167
	v_add_f32_e32 v168, 1.0, v168
	v_add_f32_e32 v169, 1.0, v169
	v_add_f32_e32 v170, 1.0, v170
	v_add_f32_e32 v171, 1.0, v171
	v_add_f32_e32 v172, 1.0, v172
	v_rcp_f32_e32 v173, v173
	v_rcp_f32_e32 v166, v166
	v_rcp_f32_e32 v167, v167
	v_rcp_f32_e32 v168, v168
	v_rcp_f32_e32 v169, v169
	v_rcp_f32_e32 v170, v170
	v_rcp_f32_e32 v171, v171
	v_rcp_f32_e32 v172, v172
	v_mul_f32_e32 v125, v125, v173
	v_mul_f32_e32 v126, v126, v166
	v_mul_f32_e32 v127, v127, v167
	v_mul_f32_e32 v128, v128, v168
	v_mul_f32_e32 v129, v129, v169
	v_mul_f32_e32 v122, v122, v170
	v_mul_f32_e32 v123, v123, v171
	v_mul_f32_e32 v124, v124, v172
	v_mul_f32_e32 v117, v117, v125
	v_mul_f32_e32 v118, v118, v126
	v_mul_f32_e32 v119, v119, v127
	v_mul_f32_e32 v120, v120, v128
	v_mul_f32_e32 v121, v121, v129
	v_mul_f32_e32 v122, v114, v122
	v_mul_f32_e32 v123, v115, v123
	v_mul_f32_e32 v124, v116, v124
	v_cvt_pk_bf16_f32 v114, v118, v119
	v_cvt_pk_bf16_f32 v115, v120, v121
	v_cvt_pk_bf16_f32 v116, v122, v123
	v_cvt_pk_bf16_f32 v117, v124, v117
	ds_write_b128 v160, v[114:117]
	ds_read_b128 v[116:119], v161
	v_mad_i64_i32 v[114:115], s[28:29], v149, s55, v[164:165]
	v_lshl_add_u64 v[114:115], s[4:5], 1, v[114:115]
	v_lshl_add_u64 v[114:115], v[114:115], 0, s[6:7]
	v_lshl_add_u64 v[114:115], v[114:115], 0, v[138:139]
	s_waitcnt lgkmcnt(0)
	global_store_dwordx4 v[114:115], v[116:119], off
	s_nop 1
	s_waitcnt vmcnt(7)
	v_fmamk_f32 v116, v201, 0x3a800000, v159
	v_rsq_f32_e32 v116, v116
	s_nop 0
	v_pk_mul_f32 v[108:109], v[108:109], v[116:117] op_sel_hi:[1,0]
	v_pk_mul_f32 v[112:113], v[112:113], v[116:117] op_sel_hi:[1,0]
	v_pk_mul_f32 v[110:111], v[110:111], v[116:117] op_sel_hi:[1,0]
	v_pk_mul_f32 v[106:107], v[106:107], v[116:117] op_sel_hi:[1,0]
	v_mul_f32_e32 v123, 0xbfb8aa3b, v109
	v_pk_mul_f32 v[104:105], v[104:105], v[116:117] op_sel_hi:[1,0]
	v_pk_mul_f32 v[102:103], v[102:103], v[116:117] op_sel_hi:[1,0]
	v_pk_mul_f32 v[100:101], v[100:101], v[116:117] op_sel_hi:[1,0]
	v_pk_mul_f32 v[98:99], v[98:99], v[116:117] op_sel_hi:[1,0]
	v_mul_f32_e32 v116, 0xbfb8aa3b, v110
	v_mul_f32_e32 v117, 0xbfb8aa3b, v111
	v_mul_f32_e32 v118, 0xbfb8aa3b, v112
	v_mul_f32_e32 v119, 0xbfb8aa3b, v113
	v_mul_f32_e32 v120, 0xbfb8aa3b, v106
	v_mul_f32_e32 v121, 0xbfb8aa3b, v107
	v_mul_f32_e32 v122, 0xbfb8aa3b, v108
	v_exp_f32_e32 v123, v123
	v_exp_f32_e32 v116, v116
	v_exp_f32_e32 v117, v117
	v_exp_f32_e32 v118, v118
	v_exp_f32_e32 v119, v119
	v_exp_f32_e32 v120, v120
	v_exp_f32_e32 v121, v121
	v_exp_f32_e32 v122, v122
	v_add_f32_e32 v123, 1.0, v123
	v_add_f32_e32 v116, 1.0, v116
	v_add_f32_e32 v117, 1.0, v117
	v_add_f32_e32 v118, 1.0, v118
	v_add_f32_e32 v119, 1.0, v119
	v_add_f32_e32 v120, 1.0, v120
	v_add_f32_e32 v121, 1.0, v121
	v_add_f32_e32 v122, 1.0, v122
	v_rcp_f32_e32 v123, v123
	v_rcp_f32_e32 v116, v116
	v_rcp_f32_e32 v117, v117
	v_rcp_f32_e32 v118, v118
	v_rcp_f32_e32 v119, v119
	v_rcp_f32_e32 v120, v120
	v_rcp_f32_e32 v121, v121
	v_rcp_f32_e32 v122, v122
	v_mul_f32_e32 v109, v109, v123
	v_mul_f32_e32 v110, v110, v116
	v_mul_f32_e32 v111, v111, v117
	v_mul_f32_e32 v112, v112, v118
	v_mul_f32_e32 v113, v113, v119
	v_mul_f32_e32 v106, v106, v120
	v_mul_f32_e32 v107, v107, v121
	v_mul_f32_e32 v108, v108, v122
	v_mul_f32_e32 v101, v101, v109
	v_mul_f32_e32 v102, v102, v110
	v_mul_f32_e32 v103, v103, v111
	v_mul_f32_e32 v104, v104, v112
	v_mul_f32_e32 v105, v105, v113
	v_mul_f32_e32 v106, v98, v106
	v_mul_f32_e32 v107, v99, v107
	v_mul_f32_e32 v108, v100, v108
	v_cvt_pk_bf16_f32 v98, v102, v103
	v_cvt_pk_bf16_f32 v99, v104, v105
	v_cvt_pk_bf16_f32 v100, v106, v107
	v_cvt_pk_bf16_f32 v101, v108, v101
	ds_write_b128 v162, v[98:101]
	ds_read_b128 v[98:101], v163
	v_add_co_u32_e32 v102, vcc, s41, v114
	s_nop 1
	v_addc_co_u32_e32 v103, vcc, 0, v115, vcc
	s_waitcnt lgkmcnt(0)
; __device__ __forceinline__ unsigned cvt_pk_bf16(float lo, float hi) { unsigned r; asm volatile("v_cvt_pk_bf16_f32 %0, %1, %2" : "=v"(r) : "v"(lo), "v"(hi)); return r; }
; #define LAS __attribute__((address_space(3)))
; __device__ __forceinline__ float siluf_(float x) { return x * __builtin_amdgcn_rcpf(1.0f + __builtin_amdgcn_exp2f(-1.4426950408889634f * x)); }
; __device__ __forceinline__ float rstd_of(float ss) { return __builtin_amdgcn_rsqf(ss * (1.0f / DM) + EPS); }
;     __device__ __forceinline__ void operator()(const pg8::f32x4 (&acc)[2][2][4][2], const Unit& u, int wr, int wc, int fr, int fq) const {
;     ...
;             for (int m = 0; m < 4; ++m) { const int rg = ai * HALF + m * 16; const float rs = rstd_of(SS1[row0 + rg + fr]);
;                 const pg8::f32x4 g0 = acc[ai][0][m][0] * rs, g1 = acc[ai][0][m][1] * rs, u0 = acc[ai][1][m][0] * rs, u1 = acc[ai][1][m][1] * rs;
;                 u32x4 w; w.x = cvt_pk_bf16(siluf_(g0[0]) * u0[0], siluf_(g0[1]) * u0[1]); w.y = cvt_pk_bf16(siluf_(g0[2]) * u0[2], siluf_(g0[3]) * u0[3]);
;                 w.z = cvt_pk_bf16(siluf_(g1[0]) * u1[0], siluf_(g1[1]) * u1[1]); w.w = cvt_pk_bf16(siluf_(g1[2]) * u1[2], siluf_(g1[3]) * u1[3]);
;                 *(LAS u32x4*)epi_slot(W, fr, fq + 4 * (m & 1)) = w;
;                 const u32x4 o = *(const LAS u32x4*)epi_slot(W, rr, sl + 4 * (m & 1));
;                 *(u32x4*)(outp + (size_t)rg * DFF) = o; }
	global_store_dwordx4 v[102:103], v[98:101], off
	s_nop 1
	s_waitcnt vmcnt(7)
	v_fmamk_f32 v98, v202, 0x3a800000, v159
	v_rsq_f32_e32 v98, v98
	s_nop 0
	v_pk_mul_f32 v[92:93], v[92:93], v[98:99] op_sel_hi:[1,0]
	v_pk_mul_f32 v[96:97], v[96:97], v[98:99] op_sel_hi:[1,0]
	v_pk_mul_f32 v[94:95], v[94:95], v[98:99] op_sel_hi:[1,0]
	v_pk_mul_f32 v[90:91], v[90:91], v[98:99] op_sel_hi:[1,0]
	v_mul_f32_e32 v105, 0xbfb8aa3b, v93
	v_pk_mul_f32 v[88:89], v[88:89], v[98:99] op_sel_hi:[1,0]
	v_pk_mul_f32 v[86:87], v[86:87], v[98:99] op_sel_hi:[1,0]
	v_pk_mul_f32 v[84:85], v[84:85], v[98:99] op_sel_hi:[1,0]
	v_pk_mul_f32 v[82:83], v[82:83], v[98:99] op_sel_hi:[1,0]
	v_mul_f32_e32 v98, 0xbfb8aa3b, v94
	v_mul_f32_e32 v99, 0xbfb8aa3b, v95
	v_mul_f32_e32 v100, 0xbfb8aa3b, v96
	v_mul_f32_e32 v101, 0xbfb8aa3b, v97
	v_mul_f32_e32 v102, 0xbfb8aa3b, v90
	v_mul_f32_e32 v103, 0xbfb8aa3b, v91
	v_mul_f32_e32 v104, 0xbfb8aa3b, v92
	v_exp_f32_e32 v105, v105
	v_exp_f32_e32 v98, v98
	v_exp_f32_e32 v99, v99
	v_exp_f32_e32 v100, v100
	v_exp_f32_e32 v101, v101
	v_exp_f32_e32 v102, v102
	v_exp_f32_e32 v103, v103
	v_exp_f32_e32 v104, v104
	v_add_f32_e32 v105, 1.0, v105
	v_add_f32_e32 v98, 1.0, v98
	v_add_f32_e32 v99, 1.0, v99
	v_add_f32_e32 v100, 1.0, v100
	v_add_f32_e32 v101, 1.0, v101
	v_add_f32_e32 v102, 1.0, v102
	v_add_f32_e32 v103, 1.0, v103
	v_add_f32_e32 v104, 1.0, v104
	v_rcp_f32_e32 v105, v105
	v_rcp_f32_e32 v98, v98
	v_rcp_f32_e32 v99, v99
	v_rcp_f32_e32 v100, v100
	v_rcp_f32_e32 v101, v101
	v_rcp_f32_e32 v102, v102
	v_rcp_f32_e32 v103, v103
	v_rcp_f32_e32 v104, v104
	v_mul_f32_e32 v93, v93, v105
	v_mul_f32_e32 v94, v94, v98
	v_mul_f32_e32 v95, v95, v99
	v_mul_f32_e32 v96, v96, v100
	v_mul_f32_e32 v97, v97, v101
	v_mul_f32_e32 v90, v90, v102
	v_mul_f32_e32 v91, v91, v103
	v_mul_f32_e32 v92, v92, v104
	v_mul_f32_e32 v85, v85, v93
	v_mul_f32_e32 v86, v86, v94
	v_mul_f32_e32 v87, v87, v95
	v_mul_f32_e32 v88, v88, v96
	v_mul_f32_e32 v89, v89, v97
	v_mul_f32_e32 v90, v82, v90
	v_mul_f32_e32 v91, v83, v91
	v_mul_f32_e32 v92, v84, v92
	v_cvt_pk_bf16_f32 v82, v86, v87
	v_cvt_pk_bf16_f32 v83, v88, v89
	v_cvt_pk_bf16_f32 v84, v90, v91
	v_cvt_pk_bf16_f32 v85, v92, v85
	ds_write_b128 v160, v[82:85]
	ds_read_b128 v[82:85], v161
	v_add_co_u32_e32 v86, vcc, s58, v114
	s_nop 1
	v_addc_co_u32_e32 v87, vcc, 0, v115, vcc
	s_waitcnt lgkmcnt(0)
	global_store_dwordx4 v[86:87], v[82:85], off
	s_nop 1
	s_waitcnt vmcnt(7)
	v_fmamk_f32 v82, v203, 0x3a800000, v159
	v_rsq_f32_e32 v82, v82
	s_nop 0
	v_pk_mul_f32 v[76:77], v[76:77], v[82:83] op_sel_hi:[1,0]
	v_pk_mul_f32 v[80:81], v[80:81], v[82:83] op_sel_hi:[1,0]
	v_pk_mul_f32 v[78:79], v[78:79], v[82:83] op_sel_hi:[1,0]
	v_pk_mul_f32 v[74:75], v[74:75], v[82:83] op_sel_hi:[1,0]
	v_mul_f32_e32 v91, 0xbfb8aa3b, v77
	v_pk_mul_f32 v[72:73], v[72:73], v[82:83] op_sel_hi:[1,0]
	v_pk_mul_f32 v[70:71], v[70:71], v[82:83] op_sel_hi:[1,0]
	v_pk_mul_f32 v[68:69], v[68:69], v[82:83] op_sel_hi:[1,0]
	v_pk_mul_f32 v[66:67], v[66:67], v[82:83] op_sel_hi:[1,0]
	v_mul_f32_e32 v82, 0xbfb8aa3b, v78
	v_mul_f32_e32 v83, 0xbfb8aa3b, v79
	v_mul_f32_e32 v86, 0xbfb8aa3b, v80
	v_mul_f32_e32 v87, 0xbfb8aa3b, v81
	v_mul_f32_e32 v88, 0xbfb8aa3b, v74
	v_mul_f32_e32 v89, 0xbfb8aa3b, v75
	v_mul_f32_e32 v90, 0xbfb8aa3b, v76
	v_exp_f32_e32 v91, v91
	v_exp_f32_e32 v82, v82
	v_exp_f32_e32 v83, v83
	v_exp_f32_e32 v86, v86
	v_exp_f32_e32 v87, v87
	v_exp_f32_e32 v88, v88
	v_exp_f32_e32 v89, v89
	v_exp_f32_e32 v90, v90
	v_add_f32_e32 v91, 1.0, v91
	v_add_f32_e32 v82, 1.0, v82
	v_add_f32_e32 v83, 1.0, v83
	v_add_f32_e32 v86, 1.0, v86
	v_add_f32_e32 v87, 1.0, v87
	v_add_f32_e32 v88, 1.0, v88
	v_add_f32_e32 v89, 1.0, v89
	v_add_f32_e32 v90, 1.0, v90
	v_rcp_f32_e32 v91, v91
	v_rcp_f32_e32 v82, v82
	v_rcp_f32_e32 v83, v83
	v_rcp_f32_e32 v86, v86
	v_rcp_f32_e32 v87, v87
	v_rcp_f32_e32 v88, v88
	v_rcp_f32_e32 v89, v89
	v_rcp_f32_e32 v90, v90
	v_mul_f32_e32 v77, v77, v91
	v_mul_f32_e32 v78, v78, v82
	v_mul_f32_e32 v79, v79, v83
	v_mul_f32_e32 v80, v80, v86
	v_mul_f32_e32 v81, v81, v87
	v_mul_f32_e32 v74, v74, v88
	v_mul_f32_e32 v75, v75, v89
	v_mul_f32_e32 v76, v76, v90
	v_mul_f32_e32 v69, v69, v77
	v_mul_f32_e32 v70, v70, v78
	v_mul_f32_e32 v71, v71, v79
	v_mul_f32_e32 v72, v72, v80
	v_mul_f32_e32 v73, v73, v81
	v_mul_f32_e32 v74, v66, v74
	v_mul_f32_e32 v75, v67, v75
	v_mul_f32_e32 v76, v68, v76
	v_cvt_pk_bf16_f32 v66, v70, v71
	v_cvt_pk_bf16_f32 v67, v72, v73
	v_cvt_pk_bf16_f32 v68, v74, v75
	v_cvt_pk_bf16_f32 v69, v76, v69
	ds_write_b128 v162, v[66:69]
	ds_read_b128 v[66:69], v163
	v_add_co_u32_e32 v70, vcc, s59, v114
	s_nop 1
	v_addc_co_u32_e32 v71, vcc, 0, v115, vcc
	s_waitcnt lgkmcnt(0)
	global_store_dwordx4 v[70:71], v[66:69], off
	s_nop 1
	s_waitcnt vmcnt(7)
; __device__ __forceinline__ unsigned cvt_pk_bf16(float lo, float hi) { unsigned r; asm volatile("v_cvt_pk_bf16_f32 %0, %1, %2" : "=v"(r) : "v"(lo), "v"(hi)); return r; }
; #define LAS __attribute__((address_space(3)))
; __device__ __forceinline__ float siluf_(float x) { return x * __builtin_amdgcn_rcpf(1.0f + __builtin_amdgcn_exp2f(-1.4426950408889634f * x)); }
; __device__ __forceinline__ float rstd_of(float ss) { return __builtin_amdgcn_rsqf(ss * (1.0f / DM) + EPS); }
;     __device__ __forceinline__ void operator()(const pg8::f32x4 (&acc)[2][2][4][2], const Unit& u, int wr, int wc, int fr, int fq) const {
;     ...
;             for (int m = 0; m < 4; ++m) { const int rg = ai * HALF + m * 16; const float rs = rstd_of(SS1[row0 + rg + fr]);
;                 const pg8::f32x4 g0 = acc[ai][0][m][0] * rs, g1 = acc[ai][0][m][1] * rs, u0 = acc[ai][1][m][0] * rs, u1 = acc[ai][1][m][1] * rs;
;                 u32x4 w; w.x = cvt_pk_bf16(siluf_(g0[0]) * u0[0], siluf_(g0[1]) * u0[1]); w.y = cvt_pk_bf16(siluf_(g0[2]) * u0[2], siluf_(g0[3]) * u0[3]);
;                 w.z = cvt_pk_bf16(siluf_(g1[0]) * u1[0], siluf_(g1[1]) * u1[1]); w.w = cvt_pk_bf16(siluf_(g1[2]) * u1[2], siluf_(g1[3]) * u1[3]);
;                 *(LAS u32x4*)epi_slot(W, fr, fq + 4 * (m & 1)) = w;
;                 const u32x4 o = *(const LAS u32x4*)epi_slot(W, rr, sl + 4 * (m & 1));
;                 *(u32x4*)(outp + (size_t)rg * DFF) = o; }
	v_fmamk_f32 v66, v204, 0x3a800000, v159
	v_rsq_f32_e32 v66, v66
	s_nop 0
	v_pk_mul_f32 v[60:61], v[60:61], v[66:67] op_sel_hi:[1,0]
	v_pk_mul_f32 v[64:65], v[64:65], v[66:67] op_sel_hi:[1,0]
	v_pk_mul_f32 v[62:63], v[62:63], v[66:67] op_sel_hi:[1,0]
	v_pk_mul_f32 v[58:59], v[58:59], v[66:67] op_sel_hi:[1,0]
	v_mul_f32_e32 v75, 0xbfb8aa3b, v61
	v_pk_mul_f32 v[56:57], v[56:57], v[66:67] op_sel_hi:[1,0]
	v_pk_mul_f32 v[54:55], v[54:55], v[66:67] op_sel_hi:[1,0]
	v_pk_mul_f32 v[52:53], v[52:53], v[66:67] op_sel_hi:[1,0]
	v_pk_mul_f32 v[50:51], v[50:51], v[66:67] op_sel_hi:[1,0]
	v_mul_f32_e32 v66, 0xbfb8aa3b, v62
	v_mul_f32_e32 v67, 0xbfb8aa3b, v63
	v_mul_f32_e32 v70, 0xbfb8aa3b, v64
	v_mul_f32_e32 v71, 0xbfb8aa3b, v65
	v_mul_f32_e32 v72, 0xbfb8aa3b, v58
	v_mul_f32_e32 v73, 0xbfb8aa3b, v59
	v_mul_f32_e32 v74, 0xbfb8aa3b, v60
	v_exp_f32_e32 v75, v75
	v_exp_f32_e32 v66, v66
	v_exp_f32_e32 v67, v67
	v_exp_f32_e32 v70, v70
	v_exp_f32_e32 v71, v71
	v_exp_f32_e32 v72, v72
	v_exp_f32_e32 v73, v73
	v_exp_f32_e32 v74, v74
	v_add_f32_e32 v75, 1.0, v75
	v_add_f32_e32 v66, 1.0, v66
	v_add_f32_e32 v67, 1.0, v67
	v_add_f32_e32 v70, 1.0, v70
	v_add_f32_e32 v71, 1.0, v71
	v_add_f32_e32 v72, 1.0, v72
	v_add_f32_e32 v73, 1.0, v73
	v_add_f32_e32 v74, 1.0, v74
	v_rcp_f32_e32 v75, v75
	v_rcp_f32_e32 v66, v66
	v_rcp_f32_e32 v67, v67
	v_rcp_f32_e32 v70, v70
	v_rcp_f32_e32 v71, v71
	v_rcp_f32_e32 v72, v72
	v_rcp_f32_e32 v73, v73
	v_rcp_f32_e32 v74, v74
	v_mul_f32_e32 v61, v61, v75
	v_mul_f32_e32 v62, v62, v66
	v_mul_f32_e32 v63, v63, v67
	v_mul_f32_e32 v64, v64, v70
	v_mul_f32_e32 v65, v65, v71
	v_mul_f32_e32 v58, v58, v72
	v_mul_f32_e32 v59, v59, v73
	v_mul_f32_e32 v60, v60, v74
	v_mul_f32_e32 v53, v53, v61
	v_mul_f32_e32 v54, v54, v62
	v_mul_f32_e32 v55, v55, v63
	v_mul_f32_e32 v56, v56, v64
	v_mul_f32_e32 v57, v57, v65
	v_mul_f32_e32 v58, v50, v58
	v_mul_f32_e32 v59, v51, v59
	v_mul_f32_e32 v60, v52, v60
	v_cvt_pk_bf16_f32 v50, v54, v55
	v_cvt_pk_bf16_f32 v51, v56, v57
	v_cvt_pk_bf16_f32 v52, v58, v59
	v_cvt_pk_bf16_f32 v53, v60, v53
	ds_write_b128 v160, v[50:53]
	ds_read_b128 v[50:53], v161
	v_add_co_u32_e32 v54, vcc, s60, v114
	s_nop 1
	v_addc_co_u32_e32 v55, vcc, 0, v115, vcc
	s_waitcnt lgkmcnt(0)
	global_store_dwordx4 v[54:55], v[50:53], off
	s_nop 1
	s_waitcnt vmcnt(7)
	v_fmamk_f32 v50, v205, 0x3a800000, v159
	v_rsq_f32_e32 v50, v50
	s_nop 0
	v_pk_mul_f32 v[44:45], v[44:45], v[50:51] op_sel_hi:[1,0]
	v_pk_mul_f32 v[48:49], v[48:49], v[50:51] op_sel_hi:[1,0]
	v_pk_mul_f32 v[46:47], v[46:47], v[50:51] op_sel_hi:[1,0]
	v_pk_mul_f32 v[42:43], v[42:43], v[50:51] op_sel_hi:[1,0]
	v_mul_f32_e32 v59, 0xbfb8aa3b, v45
	v_pk_mul_f32 v[40:41], v[40:41], v[50:51] op_sel_hi:[1,0]
	v_pk_mul_f32 v[38:39], v[38:39], v[50:51] op_sel_hi:[1,0]
	v_pk_mul_f32 v[36:37], v[36:37], v[50:51] op_sel_hi:[1,0]
	v_pk_mul_f32 v[34:35], v[34:35], v[50:51] op_sel_hi:[1,0]
	v_mul_f32_e32 v50, 0xbfb8aa3b, v46
	v_mul_f32_e32 v51, 0xbfb8aa3b, v47
	v_mul_f32_e32 v54, 0xbfb8aa3b, v48
	v_mul_f32_e32 v55, 0xbfb8aa3b, v49
	v_mul_f32_e32 v56, 0xbfb8aa3b, v42
	v_mul_f32_e32 v57, 0xbfb8aa3b, v43
	v_mul_f32_e32 v58, 0xbfb8aa3b, v44
	v_exp_f32_e32 v59, v59
	v_exp_f32_e32 v50, v50
	v_exp_f32_e32 v51, v51
	v_exp_f32_e32 v54, v54
	v_exp_f32_e32 v55, v55
	v_exp_f32_e32 v56, v56
	v_exp_f32_e32 v57, v57
	v_exp_f32_e32 v58, v58
	v_add_f32_e32 v59, 1.0, v59
	v_add_f32_e32 v50, 1.0, v50
	v_add_f32_e32 v51, 1.0, v51
	v_add_f32_e32 v54, 1.0, v54
	v_add_f32_e32 v55, 1.0, v55
	v_add_f32_e32 v56, 1.0, v56
	v_add_f32_e32 v57, 1.0, v57
	v_add_f32_e32 v58, 1.0, v58
	v_rcp_f32_e32 v59, v59
	v_rcp_f32_e32 v50, v50
	v_rcp_f32_e32 v51, v51
	v_rcp_f32_e32 v54, v54
	v_rcp_f32_e32 v55, v55
	v_rcp_f32_e32 v56, v56
	v_rcp_f32_e32 v57, v57
	v_rcp_f32_e32 v58, v58
	v_mul_f32_e32 v45, v45, v59
	v_mul_f32_e32 v46, v46, v50
	v_mul_f32_e32 v47, v47, v51
	v_mul_f32_e32 v48, v48, v54
	v_mul_f32_e32 v49, v49, v55
	v_mul_f32_e32 v42, v42, v56
	v_mul_f32_e32 v43, v43, v57
	v_mul_f32_e32 v44, v44, v58
	v_mul_f32_e32 v37, v37, v45
	v_mul_f32_e32 v38, v38, v46
	v_mul_f32_e32 v39, v39, v47
	v_mul_f32_e32 v40, v40, v48
	v_mul_f32_e32 v41, v41, v49
	v_mul_f32_e32 v42, v34, v42
	v_mul_f32_e32 v43, v35, v43
	v_mul_f32_e32 v44, v36, v44
	v_cvt_pk_bf16_f32 v34, v38, v39
	v_cvt_pk_bf16_f32 v35, v40, v41
	v_cvt_pk_bf16_f32 v36, v42, v43
	v_cvt_pk_bf16_f32 v37, v44, v37
	ds_write_b128 v162, v[34:37]
	ds_read_b128 v[34:37], v163
	v_add_co_u32_e32 v38, vcc, s61, v114
	s_nop 1
	v_addc_co_u32_e32 v39, vcc, 0, v115, vcc
	s_waitcnt lgkmcnt(0)
	global_store_dwordx4 v[38:39], v[34:37], off
	s_nop 1
	s_waitcnt vmcnt(7)
; __device__ __forceinline__ unsigned cvt_pk_bf16(float lo, float hi) { unsigned r; asm volatile("v_cvt_pk_bf16_f32 %0, %1, %2" : "=v"(r) : "v"(lo), "v"(hi)); return r; }
; #define PG8_WAIT_V(n) asm volatile("s_waitcnt vmcnt(" #n ")" ::: "memory")
; #define PG8_BAR __builtin_amdgcn_s_barrier()
; #define LAS __attribute__((address_space(3)))
; __device__ __forceinline__ float siluf_(float x) { return x * __builtin_amdgcn_rcpf(1.0f + __builtin_amdgcn_exp2f(-1.4426950408889634f * x)); }
; template <class Epi, class Sched, bool ALIGN_EPI = false, bool SP2 = false, bool AGM = false  >
; __device__ __forceinline__ void gemm_phase(PG8_LAS unsigned char* lds, const Gemm g, const Sched& S, const Epi& E) {
;     ...
;         if constexpr (ALIGN_EPI) { if (wr == 0) PG8_BAR; }
;         if constexpr (!Epi::AFTER_DRAIN) { E(acc, cur, wr, wc, fr, fq); S.done(cur); }
;         if (!has_next) break;
; #pragma unroll
;         for (int a = 0; a < 2; ++a)
; #pragma unroll
;             for (int b = 0; b < 2; ++b)
; #pragma unroll
;                 for (int m = 0; m < 4; ++m)
; #pragma unroll
;                     for (int n = 0; n < 2; ++n) acc[a][b][m][n] = (f32x4){0.f, 0.f, 0.f, 0.f};
;         cur = nxt; cA = nA; cB = nB; ++ui;
;         if constexpr (ALIGN_EPI) { if (wr == 1) PG8_BAR; }
;     }
;     PG8_WAIT_V(0);
;     if constexpr (!ALIGN_EPI) { if (wr == 0) PG8_BAR; }
;     PG8_BAR;
;     __device__ __forceinline__ void operator()(const pg8::f32x4 (&acc)[2][2][4][2], const Unit& u, int wr, int wc, int fr, int fq) const {
;     ...
;             for (int m = 0; m < 4; ++m) { const int rg = ai * HALF + m * 16; const float rs = rstd_of(SS1[row0 + rg + fr]);
;                 const pg8::f32x4 g0 = acc[ai][0][m][0] * rs, g1 = acc[ai][0][m][1] * rs, u0 = acc[ai][1][m][0] * rs, u1 = acc[ai][1][m][1] * rs;
;                 u32x4 w; w.x = cvt_pk_bf16(siluf_(g0[0]) * u0[0], siluf_(g0[1]) * u0[1]); w.y = cvt_pk_bf16(siluf_(g0[2]) * u0[2], siluf_(g0[3]) * u0[3]);
;                 w.z = cvt_pk_bf16(siluf_(g1[0]) * u1[0], siluf_(g1[1]) * u1[1]); w.w = cvt_pk_bf16(siluf_(g1[2]) * u1[2], siluf_(g1[3]) * u1[3]);
;                 *(LAS u32x4*)epi_slot(W, fr, fq + 4 * (m & 1)) = w;
;                 const u32x4 o = *(const LAS u32x4*)epi_slot(W, rr, sl + 4 * (m & 1));
;                 *(u32x4*)(outp + (size_t)rg * DFF) = o; }
	v_fmamk_f32 v34, v206, 0x3a800000, v159
	v_rsq_f32_e32 v34, v34
	s_nop 0
	v_pk_mul_f32 v[28:29], v[28:29], v[34:35] op_sel_hi:[1,0]
	v_pk_mul_f32 v[32:33], v[32:33], v[34:35] op_sel_hi:[1,0]
	v_pk_mul_f32 v[30:31], v[30:31], v[34:35] op_sel_hi:[1,0]
	v_pk_mul_f32 v[26:27], v[26:27], v[34:35] op_sel_hi:[1,0]
	v_mul_f32_e32 v43, 0xbfb8aa3b, v29
	v_pk_mul_f32 v[24:25], v[24:25], v[34:35] op_sel_hi:[1,0]
	v_pk_mul_f32 v[22:23], v[22:23], v[34:35] op_sel_hi:[1,0]
	v_pk_mul_f32 v[20:21], v[20:21], v[34:35] op_sel_hi:[1,0]
	v_pk_mul_f32 v[18:19], v[18:19], v[34:35] op_sel_hi:[1,0]
	v_mul_f32_e32 v34, 0xbfb8aa3b, v30
	v_mul_f32_e32 v35, 0xbfb8aa3b, v31
	v_mul_f32_e32 v38, 0xbfb8aa3b, v32
	v_mul_f32_e32 v39, 0xbfb8aa3b, v33
	v_mul_f32_e32 v40, 0xbfb8aa3b, v26
	v_mul_f32_e32 v41, 0xbfb8aa3b, v27
	v_mul_f32_e32 v42, 0xbfb8aa3b, v28
	v_exp_f32_e32 v43, v43
	v_exp_f32_e32 v34, v34
	v_exp_f32_e32 v35, v35
	v_exp_f32_e32 v38, v38
	v_exp_f32_e32 v39, v39
	v_exp_f32_e32 v40, v40
	v_exp_f32_e32 v41, v41
	v_exp_f32_e32 v42, v42
	v_add_f32_e32 v43, 1.0, v43
	v_add_f32_e32 v34, 1.0, v34
	v_add_f32_e32 v35, 1.0, v35
	v_add_f32_e32 v38, 1.0, v38
	v_add_f32_e32 v39, 1.0, v39
	v_add_f32_e32 v40, 1.0, v40
	v_add_f32_e32 v41, 1.0, v41
	v_add_f32_e32 v42, 1.0, v42
	v_rcp_f32_e32 v43, v43
	v_rcp_f32_e32 v34, v34
	v_rcp_f32_e32 v35, v35
	v_rcp_f32_e32 v38, v38
	v_rcp_f32_e32 v39, v39
	v_rcp_f32_e32 v40, v40
	v_rcp_f32_e32 v41, v41
	v_rcp_f32_e32 v42, v42
	v_mul_f32_e32 v29, v29, v43
	v_mul_f32_e32 v30, v30, v34
	v_mul_f32_e32 v31, v31, v35
	v_mul_f32_e32 v32, v32, v38
	v_mul_f32_e32 v33, v33, v39
	v_mul_f32_e32 v26, v26, v40
	v_mul_f32_e32 v27, v27, v41
	v_mul_f32_e32 v28, v28, v42
	v_mul_f32_e32 v21, v21, v29
	v_mul_f32_e32 v22, v22, v30
	v_mul_f32_e32 v23, v23, v31
	v_mul_f32_e32 v24, v24, v32
	v_mul_f32_e32 v25, v25, v33
	v_mul_f32_e32 v26, v18, v26
	v_mul_f32_e32 v27, v19, v27
	v_mul_f32_e32 v28, v20, v28
	v_cvt_pk_bf16_f32 v18, v22, v23
	v_cvt_pk_bf16_f32 v19, v24, v25
	v_cvt_pk_bf16_f32 v20, v26, v27
	v_cvt_pk_bf16_f32 v21, v28, v21
	ds_write_b128 v160, v[18:21]
	ds_read_b128 v[18:21], v161
	v_add_co_u32_e32 v22, vcc, s62, v114
	s_nop 1
	v_addc_co_u32_e32 v23, vcc, 0, v115, vcc
	s_waitcnt lgkmcnt(0)
	global_store_dwordx4 v[22:23], v[18:21], off
	s_nop 1
	v_add_co_u32_e32 v20, vcc, 0xf2000, v114
	s_waitcnt vmcnt(7)
	v_fmamk_f32 v18, v207, 0x3a800000, v159
	v_rsq_f32_e32 v18, v18
	s_nop 0
	v_pk_mul_f32 v[12:13], v[12:13], v[18:19] op_sel_hi:[1,0]
	v_pk_mul_f32 v[16:17], v[16:17], v[18:19] op_sel_hi:[1,0]
	v_pk_mul_f32 v[14:15], v[14:15], v[18:19] op_sel_hi:[1,0]
	v_pk_mul_f32 v[10:11], v[10:11], v[18:19] op_sel_hi:[1,0]
	v_mul_f32_e32 v26, 0xbfb8aa3b, v13
	v_pk_mul_f32 v[8:9], v[8:9], v[18:19] op_sel_hi:[1,0]
	v_pk_mul_f32 v[6:7], v[6:7], v[18:19] op_sel_hi:[1,0]
	v_pk_mul_f32 v[4:5], v[4:5], v[18:19] op_sel_hi:[1,0]
	v_pk_mul_f32 v[2:3], v[2:3], v[18:19] op_sel_hi:[1,0]
	v_mul_f32_e32 v18, 0xbfb8aa3b, v14
	v_mul_f32_e32 v19, 0xbfb8aa3b, v15
	v_mul_f32_e32 v21, 0xbfb8aa3b, v16
	v_mul_f32_e32 v22, 0xbfb8aa3b, v17
	v_mul_f32_e32 v23, 0xbfb8aa3b, v10
	v_mul_f32_e32 v24, 0xbfb8aa3b, v11
	v_mul_f32_e32 v25, 0xbfb8aa3b, v12
	v_exp_f32_e32 v26, v26
	v_exp_f32_e32 v18, v18
	v_exp_f32_e32 v19, v19
	v_exp_f32_e32 v21, v21
	v_exp_f32_e32 v22, v22
	v_exp_f32_e32 v23, v23
	v_exp_f32_e32 v24, v24
	v_exp_f32_e32 v25, v25
	v_add_f32_e32 v26, 1.0, v26
	v_add_f32_e32 v18, 1.0, v18
	v_add_f32_e32 v19, 1.0, v19
	v_add_f32_e32 v21, 1.0, v21
	v_add_f32_e32 v22, 1.0, v22
	v_add_f32_e32 v23, 1.0, v23
	v_add_f32_e32 v24, 1.0, v24
	v_add_f32_e32 v25, 1.0, v25
	v_rcp_f32_e32 v26, v26
	v_rcp_f32_e32 v18, v18
	v_rcp_f32_e32 v19, v19
	v_rcp_f32_e32 v21, v21
	v_rcp_f32_e32 v22, v22
	v_rcp_f32_e32 v23, v23
	v_rcp_f32_e32 v24, v24
	v_rcp_f32_e32 v25, v25
	v_mul_f32_e32 v13, v13, v26
	v_mul_f32_e32 v14, v14, v18
	v_mul_f32_e32 v15, v15, v19
	v_mul_f32_e32 v16, v16, v21
	v_mul_f32_e32 v17, v17, v22
	v_mul_f32_e32 v10, v10, v23
	v_mul_f32_e32 v11, v11, v24
	v_mul_f32_e32 v12, v12, v25
	v_mul_f32_e32 v5, v5, v13
	v_mul_f32_e32 v6, v6, v14
	v_mul_f32_e32 v7, v7, v15
	v_mul_f32_e32 v8, v8, v16
	v_mul_f32_e32 v9, v9, v17
	v_mul_f32_e32 v10, v2, v10
	v_mul_f32_e32 v11, v3, v11
	v_mul_f32_e32 v12, v4, v12
	v_cvt_pk_bf16_f32 v2, v6, v7
	v_cvt_pk_bf16_f32 v3, v8, v9
	v_cvt_pk_bf16_f32 v4, v10, v11
	v_cvt_pk_bf16_f32 v5, v12, v5
	ds_write_b128 v162, v[2:5]
	ds_read_b128 v[2:5], v163
	v_addc_co_u32_e32 v21, vcc, 0, v115, vcc
	s_andn2_b64 vcc, exec, s[0:1]
	s_mov_b64 s[0:1], -1
	s_waitcnt lgkmcnt(0)
	global_store_dwordx4 v[20:21], v[2:5], off
	s_cbranch_vccnz .LBB0_873
	s_andn2_b64 vcc, exec, s[12:13]
	s_cbranch_vccnz .LBB0_872
	s_branch .LBB0_872
.LBB0_883:
	s_and_b64 vcc, exec, s[18:19]
	s_cbranch_vccz .Lp6_noalign_skip
	s_barrier
.Lp6_noalign_skip:
	s_waitcnt vmcnt(0)
	s_barrier
